# attention: first two K-fragment reads of the next QK issued right after the barrier, ahead of the slow V ds_write_b128s (re-issued after the rescale path)
# speedup vs baseline: 1.0034x; 1.0034x over previous
; #define SBAR() __builtin_amdgcn_sched_barrier(0)
; #define KWRITE(b, src0, src1) do { if constexpr (ND0 == 4) { *(bf16x8*)(K_lds + (b) * SHM_K + KSWZ(kr, kcb)) = src0; } \
;     else { int kc = sc * 2; *(bf16x8*)(K_lds + (b) * SHM_K + KSWZ(sr, kc)) = src0; *(bf16x8*)(K_lds + (b) * SHM_K + KSWZ(32 + sr, kc)) = src1; } } while (0)
; #define SLOAD_A(k0) do { vs0a = *reinterpret_cast<const bf16x8*>(&Vh[(long)((k0) + sr) * LDK + sc]); vs1a = *reinterpret_cast<const bf16x8*>(&Vh[(long)((k0) + 32 + sr) * LDK + sc]); KLOAD(ks0a, ks1a, k0); } while (0)
; #define SLOAD_B(k0) do { vs0b = *reinterpret_cast<const bf16x8*>(&Vh[(long)((k0) + sr) * LDK + sc]); vs1b = *reinterpret_cast<const bf16x8*>(&Vh[(long)((k0) + 32 + sr) * LDK + sc]); KLOAD(ks0b, ks1b, k0); } while (0)
; #define SWRITE_A(b) do { *(bf16x8*)(V_lds + (b) * SHM_V + vst0) = vs0a; *(bf16x8*)(V_lds + (b) * SHM_V + vst1) = vs1a; KWRITE(b, ks0a, ks1a); } while (0)
; #define SWRITE_B(b) do { *(bf16x8*)(V_lds + (b) * SHM_V + vst0) = vs0b; *(bf16x8*)(V_lds + (b) * SHM_V + vst1) = vs1b; KWRITE(b, ks0b, ks1b); } while (0)
; __device__ __forceinline__ void partialSM_pre(f32x16& p0, f32x16& p1, float& m_ref, float& alpha, const float thr2) {
;     ...
; #pragma unroll
;   for (int r = 0; r < 16; ++r) p0[r] = __builtin_amdgcn_exp2f(p0[r]);
; template <int ND0, int LDQ, int LDK, int LDO> ...
;     ...
;   f32x16 pA0, pA1, pB0, pB1; float mnA, mnB, alA, alB; bf16x8 pa0, pa1, pa2, pa3; const int NT = seq / KVBLK;
;   const char* Kq0 = K_lds + kofs; const char* Kq1 = K_lds + SHM_K + kofs;
;   if (ND0 == 4 && have_pf) { vs0a = pfv0; vs1a = pfv1; ks0a = pfk0; } else { SLOAD_A(0); }
;   asm volatile("s_waitcnt vmcnt(0)" ::: "memory"); SWRITE_A(0); __syncthreads();
;   qkt<ND0>(pA0, pA1, Kq0, qr, r32, hi); PSM(pA0, pA1, mnA, alA);
;   SLOAD_B(KVBLK); if (2 < NT) SLOAD_A(2 * KVBLK);
;   SWAIT(); SWRITE_B(1); __syncthreads();
;   for (int j = 1; j + 1 < NT; j += 2) {
;     SBAR(); qkt<ND0>(pB0, pB1, Kq1, qr, r32, hi);
;     finishSM(pA0, pA1, alA, l_reg, pa0, pa1, pa2, pa3); SBAR();
;     SLOAD_B((j + 2) * KVBLK); SBAR();
;     pv_d0(o, vb0, pa0, pa1, pa2, pa3); KWRITE(0, ks0a, ks1a); PSM(pB0, pB1, mnB, alB);
;     __syncthreads(); SWAIT(); VWRITE_A(0);
;     RESC(alB); __syncthreads();
;     SBAR(); qkt<ND0>(pA0, pA1, Kq0, qr, r32, hi);
.LBB0_148:
	v_exp_f32_e32 v226, v96
	v_exp_f32_e32 v244, v97
	v_exp_f32_e32 v224, v98
	v_exp_f32_e32 v227, v99
	v_exp_f32_e32 v223, v100
	v_exp_f32_e32 v225, v101
	v_exp_f32_e32 v221, v102
	v_exp_f32_e32 v222, v103
	v_exp_f32_e32 v218, v104
	v_exp_f32_e32 v220, v105
	v_exp_f32_e32 v217, v106
	v_exp_f32_e32 v219, v107
	v_exp_f32_e32 v214, v108
	v_exp_f32_e32 v216, v109
	v_exp_f32_e32 v213, v110
	v_exp_f32_e32 v215, v111
	s_waitcnt lgkmcnt(0)
	s_barrier
	ds_read_b128 v[64:67], v199 offset:32768
	ds_read_b128 v[68:71], v199 offset:40960
	s_waitcnt vmcnt(4)
	v_cmp_gt_f32_e32 vcc, 1.0, v210
	s_waitcnt vmcnt(4)
	ds_write_b128 v197, v[158:161]
	ds_write_b128 v198, v[154:157]
	s_cbranch_vccz .LBB0_152
	s_and_saveexec_b64 s[4:5], s[8:9]
	ds_write_b32 v190, v210 offset:128
	s_or_b64 exec, exec, s[4:5]
	s_waitcnt lgkmcnt(0)
	v_add_u32_e32 v76, v185, v112
	ds_read_b128 v[64:67], v76 offset:224
	ds_read_b128 v[68:71], v76 offset:192
	ds_read_b128 v[72:75], v76 offset:160
	ds_read_b128 v[76:79], v76 offset:128
	v_mov_b32_e32 v232, 0x80
	s_waitcnt lgkmcnt(3)
	v_pk_mul_f32 v[12:13], v[12:13], v[64:65]
	s_waitcnt lgkmcnt(2)
	v_pk_mul_f32 v[8:9], v[8:9], v[68:69]
	s_waitcnt lgkmcnt(1)
	v_pk_mul_f32 v[4:5], v[4:5], v[72:73]
	v_pk_mul_f32 v[14:15], v[14:15], v[66:67]
	v_pk_mul_f32 v[10:11], v[10:11], v[70:71]
	v_pk_mul_f32 v[6:7], v[6:7], v[74:75]
	s_waitcnt lgkmcnt(0)
	v_pk_mul_f32 v[2:3], v[2:3], v[78:79]
	v_pk_mul_f32 v[0:1], v[0:1], v[76:77]
	v_pk_mul_f32 v[60:61], v[60:61], v[64:65]
	v_pk_mul_f32 v[56:57], v[56:57], v[68:69]
	v_pk_mul_f32 v[52:53], v[52:53], v[72:73]
	v_pk_mul_f32 v[62:63], v[62:63], v[66:67]
	v_pk_mul_f32 v[58:59], v[58:59], v[70:71]
	v_pk_mul_f32 v[54:55], v[54:55], v[74:75]
	v_pk_mul_f32 v[50:51], v[50:51], v[78:79]
	v_pk_mul_f32 v[48:49], v[48:49], v[76:77]
	v_pk_mul_f32 v[44:45], v[44:45], v[64:65]
	v_pk_mul_f32 v[40:41], v[40:41], v[68:69]
	v_pk_mul_f32 v[36:37], v[36:37], v[72:73]
	v_pk_mul_f32 v[46:47], v[46:47], v[66:67]
	v_pk_mul_f32 v[42:43], v[42:43], v[70:71]
	v_pk_mul_f32 v[38:39], v[38:39], v[74:75]
	v_pk_mul_f32 v[34:35], v[34:35], v[78:79]
	v_pk_mul_f32 v[32:33], v[32:33], v[76:77]
	v_pk_mul_f32 v[28:29], v[28:29], v[64:65]
	v_pk_mul_f32 v[24:25], v[24:25], v[68:69]
	v_pk_mul_f32 v[20:21], v[20:21], v[72:73]
	v_pk_mul_f32 v[30:31], v[30:31], v[66:67]
	v_pk_mul_f32 v[26:27], v[26:27], v[70:71]
	v_pk_mul_f32 v[22:23], v[22:23], v[74:75]
	v_pk_mul_f32 v[18:19], v[18:19], v[78:79]
	v_pk_mul_f32 v[16:17], v[16:17], v[76:77]
	ds_read_b128 v[64:67], v199 offset:32768
	ds_read_b128 v[68:71], v199 offset:40960
	s_waitcnt lgkmcnt(0)
	s_branch .LBB0_153

; #define SBAR() __builtin_amdgcn_sched_barrier(0)
; #define KWRITE(b, src0, src1) do { if constexpr (ND0 == 4) { *(bf16x8*)(K_lds + (b) * SHM_K + KSWZ(kr, kcb)) = src0; } \
;     else { int kc = sc * 2; *(bf16x8*)(K_lds + (b) * SHM_K + KSWZ(sr, kc)) = src0; *(bf16x8*)(K_lds + (b) * SHM_K + KSWZ(32 + sr, kc)) = src1; } } while (0)
; #define SLOAD_A(k0) do { vs0a = *reinterpret_cast<const bf16x8*>(&Vh[(long)((k0) + sr) * LDK + sc]); vs1a = *reinterpret_cast<const bf16x8*>(&Vh[(long)((k0) + 32 + sr) * LDK + sc]); KLOAD(ks0a, ks1a, k0); } while (0)
; #define PSM(P0, P1, MN, AL) do { if constexpr (PRE) partialSM_pre(P0, P1, m_reg, AL, 11.541560327111707f); else partialSM(P0, P1, m_reg, MN, AL, C, thr_raw); } while (0)
; __device__ __forceinline__ void finishSM(f32x16& p0, f32x16& p1, float alpha, float& l_reg, bf16x8& pa0, bf16x8& pa1, bf16x8& pa2, bf16x8& pa3) {
; #pragma unroll
;   for (int r = 0; r < 16; ++r) p1[r] = __builtin_amdgcn_exp2f(p1[r]);
;   float ps = 0;
; #pragma unroll
;   for (int r = 0; r < 16; ++r) ps += p0[r];
; #pragma unroll
;   for (int r = 0; r < 16; ++r) ps += p1[r];
;   { auto rr = __builtin_amdgcn_permlane32_swap(__float_as_uint(ps), __float_as_uint(ps), false, false);
;     ps = __uint_as_float(rr[0]) + __uint_as_float(rr[1]); }
;   l_reg = l_reg * alpha + ps;
;     ...
;   PK4(p0, 0, pa0); PK4(p0, 8, pa1); PK4(p1, 0, pa2); PK4(p1, 8, pa3);
;     ...
; }
; template <int ND0>
; __device__ __forceinline__ void qkt(f32x16& p0, f32x16& p1, const char* Ks, const bf16x8* qr, int r32, int hi) {
;   p0 = f32x16{}; p1 = f32x16{};
; #pragma unroll
;   for (int d0 = 0; d0 < ND0; ++d0) { int cb = (d0 * 16 + hi * 8) * 2;
;     bf16x8 b0 = *reinterpret_cast<const bf16x8*>(Ks + KSWZ(r32, cb));
;     bf16x8 b1 = *reinterpret_cast<const bf16x8*>(Ks + KSWZ(32 + r32, cb));
;     p0 = __builtin_amdgcn_mfma_f32_32x32x16_bf16(b0, qr[d0], p0, 0, 0, 0);
;     p1 = __builtin_amdgcn_mfma_f32_32x32x16_bf16(b1, qr[d0], p1, 0, 0, 0); }
; }
; template <int ND0, int LDQ, int LDK, int LDO> ...
;     ...
;     SBAR(); qkt<ND0>(pA0, pA1, Kq0, qr, r32, hi);
;     finishSM(pB0, pB1, alB, l_reg, pa0, pa1, pa2, pa3); SBAR();
;     if (j + 3 < NT) SLOAD_A((j + 3) * KVBLK); SBAR();
;     pv_d0(o, vb0 + (int)SHM_V, pa0, pa1, pa2, pa3); KWRITE(1, ks0b, ks1b); PSM(pA0, pA1, mnA, alA);
.LBB0_153:
	v_mov_b32_e32 v242, 0x800
	ds_read_b128 v[238:241], v200 offset:32768
	ds_read_b128 v[234:237], v200 offset:40960
	v_exp_f32_e32 v245, v88
	v_exp_f32_e32 v246, v89
	s_waitcnt lgkmcnt(2)
	v_mfma_f32_32x32x16_bf16 v[96:111], v[64:67], v[114:117], 0
	v_exp_f32_e32 v247, v90
	v_exp_f32_e32 v231, v91
	v_exp_f32_e32 v243, v92
	v_exp_f32_e32 v252, v93
	v_exp_f32_e32 v253, v94
	v_exp_f32_e32 v95, v95
	v_mfma_f32_32x32x16_bf16 v[64:79], v[68:71], v[114:117], 0
	s_waitcnt lgkmcnt(0)
	v_mfma_f32_32x32x16_bf16 v[96:111], v[238:241], v[122:125], v[96:111]
	v_mfma_f32_32x32x16_bf16 v[64:79], v[234:237], v[122:125], v[64:79]
	ds_read_b128 v[234:237], v202 offset:32768
	ds_read_b128 v[238:241], v202 offset:40960
	s_waitcnt lgkmcnt(0)
	v_mfma_f32_32x32x16_bf16 v[96:111], v[234:237], v[142:145], v[96:111]
	v_mfma_f32_32x32x16_bf16 v[64:79], v[238:241], v[142:145], v[64:79]
	ds_read_b128 v[234:237], v201 offset:32768
	ds_read_b128 v[238:241], v201 offset:40960
	s_waitcnt lgkmcnt(0)
	v_mfma_f32_32x32x16_bf16 v[96:111], v[234:237], v[138:141], v[96:111]
	v_mfma_f32_32x32x16_bf16 v[64:79], v[238:241], v[138:141], v[64:79]
	ds_read_b128 v[234:237], v203 offset:32768
	ds_read_b128 v[238:241], v203 offset:40960
	s_waitcnt lgkmcnt(0)
	v_mfma_f32_32x32x16_bf16 v[96:111], v[234:237], v[134:137], v[96:111]
	v_mfma_f32_32x32x16_bf16 v[64:79], v[238:241], v[134:137], v[64:79]
	ds_read_b128 v[234:237], v204 offset:32768
	ds_read_b128 v[238:241], v204 offset:40960
	s_waitcnt lgkmcnt(0)
	v_mfma_f32_32x32x16_bf16 v[96:111], v[234:237], v[130:133], v[96:111]
	v_mfma_f32_32x32x16_bf16 v[64:79], v[238:241], v[130:133], v[64:79]
	ds_read_b128 v[234:237], v206 offset:32768
	ds_read_b128 v[238:241], v206 offset:40960
	s_waitcnt lgkmcnt(0)
	v_mfma_f32_32x32x16_bf16 v[96:111], v[234:237], v[126:129], v[96:111]
	v_mfma_f32_32x32x16_bf16 v[64:79], v[238:241], v[126:129], v[64:79]
	ds_read_b128 v[234:237], v205 offset:32768
	ds_read_b128 v[238:241], v205 offset:40960
	s_waitcnt lgkmcnt(0)
	v_mfma_f32_32x32x16_bf16 v[96:111], v[234:237], v[118:121], v[96:111]
	v_exp_f32_e32 v234, v80
	v_add_f32_e32 v80, 0, v226
	v_add_f32_e32 v80, v244, v80
	v_add_f32_e32 v80, v224, v80
	v_add_f32_e32 v80, v227, v80
	v_add_f32_e32 v80, v223, v80
	v_add_f32_e32 v80, v225, v80
	v_add_f32_e32 v80, v221, v80
	v_add_f32_e32 v80, v222, v80
	v_add_f32_e32 v80, v218, v80
	v_add_f32_e32 v80, v220, v80
	v_add_f32_e32 v80, v217, v80
	v_add_f32_e32 v80, v219, v80
	v_add_f32_e32 v80, v214, v80
	v_exp_f32_e32 v235, v81
	v_add_f32_e32 v80, v216, v80
	v_exp_f32_e32 v236, v82
	v_add_f32_e32 v80, v213, v80
	v_exp_f32_e32 v237, v83
	v_add_f32_e32 v80, v215, v80
	v_mfma_f32_32x32x16_bf16 v[64:79], v[238:241], v[118:121], v[64:79]
	v_exp_f32_e32 v238, v84
	v_add_f32_e32 v80, v234, v80
	v_exp_f32_e32 v239, v85
	v_add_f32_e32 v80, v235, v80
	v_exp_f32_e32 v240, v86
	v_add_f32_e32 v80, v236, v80
	v_exp_f32_e32 v241, v87
	v_add_f32_e32 v80, v237, v80
	v_add_f32_e32 v80, v238, v80
	v_add_f32_e32 v80, v239, v80
	v_add_f32_e32 v80, v240, v80
	v_add_f32_e32 v80, v241, v80
	v_add_f32_e32 v80, v245, v80
	v_add_f32_e32 v80, v246, v80
	v_add_f32_e32 v80, v247, v80
	v_add_f32_e32 v80, v231, v80
	v_add_f32_e32 v80, v243, v80
	v_add_f32_e32 v80, v252, v80
	v_add_f32_e32 v80, v253, v80
	v_add_f32_e32 v211, v95, v80
	v_mov_b32_e32 v212, v211
	v_cvt_pk_bf16_f32 v80, v226, v244
	v_cvt_pk_bf16_f32 v81, v224, v227
	v_cvt_pk_bf16_f32 v82, v223, v225
	v_cvt_pk_bf16_f32 v83, v221, v222
	v_cvt_pk_bf16_f32 v84, v218, v220
	v_cvt_pk_bf16_f32 v85, v217, v219
	v_cvt_pk_bf16_f32 v86, v214, v216
	v_cvt_pk_bf16_f32 v87, v213, v215
	v_cvt_pk_bf16_f32 v88, v234, v235
	v_cvt_pk_bf16_f32 v89, v236, v237
	v_cvt_pk_bf16_f32 v90, v238, v239
	v_cvt_pk_bf16_f32 v91, v240, v241
	v_cvt_pk_bf16_f32 v92, v245, v246
	v_cvt_pk_bf16_f32 v93, v247, v231
	v_cvt_pk_bf16_f32 v94, v243, v252
	v_cvt_pk_bf16_f32 v95, v253, v95
	v_permlane32_swap_b32_e32 v211, v212
	v_permlane32_swap_b32_e32 v80, v82
	v_permlane32_swap_b32_e32 v81, v83
	v_permlane32_swap_b32_e32 v84, v86
	v_permlane32_swap_b32_e32 v85, v87
	v_permlane32_swap_b32_e32 v88, v90
	v_permlane32_swap_b32_e32 v89, v91
	v_permlane32_swap_b32_e32 v92, v94
	v_permlane32_swap_b32_e32 v93, v95
	s_add_i32 s39, s39, 2
	s_cmp_ge_u32 s39, s38
	s_cselect_b64 s[4:5], -1, 0
	s_and_b64 vcc, exec, s[4:5]
	s_cbranch_vccnz .Lgqa_pf_skip
	v_add_co_u32_e32 v146, vcc, 0xfffe8000, v188
	s_nop 1
	v_addc_co_u32_e32 v147, vcc, -1, v189, vcc
	global_load_dwordx4 v[158:161], v[146:147], off
	global_load_dwordx4 v[150:153], v[146:147], off offset:-512
	global_load_dwordx4 v[154:157], v[188:189], off
	global_load_dwordx4 v[146:149], v[188:189], off offset:-512

; #define SBAR() __builtin_amdgcn_sched_barrier(0)
; #define KWRITE(b, src0, src1) do { if constexpr (ND0 == 4) { *(bf16x8*)(K_lds + (b) * SHM_K + KSWZ(kr, kcb)) = src0; } \
;     else { int kc = sc * 2; *(bf16x8*)(K_lds + (b) * SHM_K + KSWZ(sr, kc)) = src0; *(bf16x8*)(K_lds + (b) * SHM_K + KSWZ(32 + sr, kc)) = src1; } } while (0)
; #define SLOAD_A(k0) do { vs0a = *reinterpret_cast<const bf16x8*>(&Vh[(long)((k0) + sr) * LDK + sc]); vs1a = *reinterpret_cast<const bf16x8*>(&Vh[(long)((k0) + 32 + sr) * LDK + sc]); KLOAD(ks0a, ks1a, k0); } while (0)
; #define SLOAD_B(k0) do { vs0b = *reinterpret_cast<const bf16x8*>(&Vh[(long)((k0) + sr) * LDK + sc]); vs1b = *reinterpret_cast<const bf16x8*>(&Vh[(long)((k0) + 32 + sr) * LDK + sc]); KLOAD(ks0b, ks1b, k0); } while (0)
; #define SWRITE_A(b) do { *(bf16x8*)(V_lds + (b) * SHM_V + vst0) = vs0a; *(bf16x8*)(V_lds + (b) * SHM_V + vst1) = vs1a; KWRITE(b, ks0a, ks1a); } while (0)
; #define SWRITE_B(b) do { *(bf16x8*)(V_lds + (b) * SHM_V + vst0) = vs0b; *(bf16x8*)(V_lds + (b) * SHM_V + vst1) = vs1b; KWRITE(b, ks0b, ks1b); } while (0)
; template <int ND0, int LDQ, int LDK, int LDO> ...
;     ...
;   f32x16 pA0, pA1, pB0, pB1; float mnA, mnB, alA, alB; bf16x8 pa0, pa1, pa2, pa3; const int NT = seq / KVBLK;
;   const char* Kq0 = K_lds + kofs; const char* Kq1 = K_lds + SHM_K + kofs;
;   if (ND0 == 4 && have_pf) { vs0a = pfv0; vs1a = pfv1; ks0a = pfk0; } else { SLOAD_A(0); }
;   asm volatile("s_waitcnt vmcnt(0)" ::: "memory"); SWRITE_A(0); __syncthreads();
;   qkt<ND0>(pA0, pA1, Kq0, qr, r32, hi); PSM(pA0, pA1, mnA, alA);
;   SLOAD_B(KVBLK); if (2 < NT) SLOAD_A(2 * KVBLK);
;   SWAIT(); SWRITE_B(1); __syncthreads();
;   for (int j = 1; j + 1 < NT; j += 2) {
;     SBAR(); qkt<ND0>(pB0, pB1, Kq1, qr, r32, hi);
;     finishSM(pA0, pA1, alA, l_reg, pa0, pa1, pa2, pa3); SBAR();
;     SLOAD_B((j + 2) * KVBLK); SBAR();
;     pv_d0(o, vb0, pa0, pa1, pa2, pa3); KWRITE(0, ks0a, ks1a); PSM(pB0, pB1, mnB, alB);
;     __syncthreads(); SWAIT(); VWRITE_A(0);
;     RESC(alB); __syncthreads();
;     SBAR(); qkt<ND0>(pA0, pA1, Kq0, qr, r32, hi);
;     finishSM(pB0, pB1, alB, l_reg, pa0, pa1, pa2, pa3); SBAR();
;     if (j + 3 < NT) SLOAD_A((j + 3) * KVBLK); SBAR();
;     pv_d0(o, vb0 + (int)SHM_V, pa0, pa1, pa2, pa3); KWRITE(1, ks0b, ks1b); PSM(pA0, pA1, mnA, alA);
;     __syncthreads(); SWAIT(); VWRITE_B(1);
;     RESC(alA); __syncthreads();
;   }
.LBB0_157:
	v_exp_f32_e32 v176, v96
	v_exp_f32_e32 v213, v97
	v_exp_f32_e32 v174, v98
	v_exp_f32_e32 v177, v99
	v_exp_f32_e32 v173, v100
	v_exp_f32_e32 v175, v101
	v_exp_f32_e32 v171, v102
	v_exp_f32_e32 v172, v103
	v_add_f32_e32 v80, v208, v209
	v_fmac_f32_e32 v80, v207, v192
	v_add_f32_e32 v192, v211, v212
	v_fmac_f32_e32 v192, v80, v210
	s_waitcnt lgkmcnt(0)
	s_barrier
	ds_read_b128 v[80:83], v199 offset:49152
	ds_read_b128 v[84:87], v199 offset:57344
	s_waitcnt vmcnt(4)
	v_cmp_gt_f32_e32 vcc, 1.0, v170
	ds_write_b128 v197, v[162:165] offset:16384
	ds_write_b128 v198, v[166:169] offset:16384
	s_cbranch_vccz .LBB0_161
	s_and_saveexec_b64 s[16:17], s[8:9]
	ds_write_b32 v190, v170 offset:128
	s_or_b64 exec, exec, s[16:17]
	s_waitcnt lgkmcnt(0)
	v_add_u32_e32 v92, v185, v112
	ds_read_b128 v[80:83], v92 offset:224
	ds_read_b128 v[84:87], v92 offset:192
	ds_read_b128 v[88:91], v92 offset:160
	ds_read_b128 v[92:95], v92 offset:128
	s_waitcnt lgkmcnt(3)
	v_pk_mul_f32 v[12:13], v[12:13], v[80:81]
	s_waitcnt lgkmcnt(2)
	v_pk_mul_f32 v[8:9], v[8:9], v[84:85]
	s_waitcnt lgkmcnt(1)
	v_pk_mul_f32 v[4:5], v[4:5], v[88:89]
	v_pk_mul_f32 v[14:15], v[14:15], v[82:83]
	v_pk_mul_f32 v[10:11], v[10:11], v[86:87]
	v_pk_mul_f32 v[6:7], v[6:7], v[90:91]
	s_waitcnt lgkmcnt(0)
	v_pk_mul_f32 v[2:3], v[2:3], v[94:95]
	v_pk_mul_f32 v[0:1], v[0:1], v[92:93]
	v_pk_mul_f32 v[60:61], v[60:61], v[80:81]
	v_pk_mul_f32 v[56:57], v[56:57], v[84:85]
	v_pk_mul_f32 v[52:53], v[52:53], v[88:89]
	v_pk_mul_f32 v[62:63], v[62:63], v[82:83]
	v_pk_mul_f32 v[58:59], v[58:59], v[86:87]
	v_pk_mul_f32 v[54:55], v[54:55], v[90:91]
	v_pk_mul_f32 v[50:51], v[50:51], v[94:95]
	v_pk_mul_f32 v[48:49], v[48:49], v[92:93]
	v_pk_mul_f32 v[44:45], v[44:45], v[80:81]
	v_pk_mul_f32 v[40:41], v[40:41], v[84:85]
	v_pk_mul_f32 v[36:37], v[36:37], v[88:89]
	v_pk_mul_f32 v[46:47], v[46:47], v[82:83]
	v_pk_mul_f32 v[42:43], v[42:43], v[86:87]
	v_pk_mul_f32 v[38:39], v[38:39], v[90:91]
	v_pk_mul_f32 v[34:35], v[34:35], v[94:95]
	v_pk_mul_f32 v[32:33], v[32:33], v[92:93]
	v_pk_mul_f32 v[28:29], v[28:29], v[80:81]
	v_pk_mul_f32 v[24:25], v[24:25], v[84:85]
	v_pk_mul_f32 v[20:21], v[20:21], v[88:89]
	v_pk_mul_f32 v[30:31], v[30:31], v[82:83]
	v_pk_mul_f32 v[26:27], v[26:27], v[86:87]
	v_pk_mul_f32 v[22:23], v[22:23], v[90:91]
	v_pk_mul_f32 v[18:19], v[18:19], v[94:95]
	v_pk_mul_f32 v[16:17], v[16:17], v[92:93]
	ds_read_b128 v[80:83], v199 offset:49152
	ds_read_b128 v[84:87], v199 offset:57344
	s_waitcnt lgkmcnt(0)
.LBB0_161:
	v_exp_f32_e32 v167, v104
	v_exp_f32_e32 v169, v105
	v_exp_f32_e32 v166, v106
	v_exp_f32_e32 v168, v107
	v_exp_f32_e32 v163, v108
	v_exp_f32_e32 v165, v109
	v_exp_f32_e32 v162, v110
	v_exp_f32_e32 v164, v111
	v_lshl_add_u64 v[188:189], v[188:189], 0, s[42:43]
	s_and_b64 vcc, exec, s[4:5]
	s_cbranch_vccnz .LBB0_167
	v_mov_b32_e32 v207, v170
	s_branch .LBB0_146

; #define SBAR() __builtin_amdgcn_sched_barrier(0)
; #define KWRITE(b, src0, src1) do { if constexpr (ND0 == 4) { *(bf16x8*)(K_lds + (b) * SHM_K + KSWZ(kr, kcb)) = src0; } \
;     else { int kc = sc * 2; *(bf16x8*)(K_lds + (b) * SHM_K + KSWZ(sr, kc)) = src0; *(bf16x8*)(K_lds + (b) * SHM_K + KSWZ(32 + sr, kc)) = src1; } } while (0)
; #define SLOAD_A(k0) do { vs0a = *reinterpret_cast<const bf16x8*>(&Vh[(long)((k0) + sr) * LDK + sc]); vs1a = *reinterpret_cast<const bf16x8*>(&Vh[(long)((k0) + 32 + sr) * LDK + sc]); KLOAD(ks0a, ks1a, k0); } while (0)
; #define SLOAD_B(k0) do { vs0b = *reinterpret_cast<const bf16x8*>(&Vh[(long)((k0) + sr) * LDK + sc]); vs1b = *reinterpret_cast<const bf16x8*>(&Vh[(long)((k0) + 32 + sr) * LDK + sc]); KLOAD(ks0b, ks1b, k0); } while (0)
; #define SWRITE_A(b) do { *(bf16x8*)(V_lds + (b) * SHM_V + vst0) = vs0a; *(bf16x8*)(V_lds + (b) * SHM_V + vst1) = vs1a; KWRITE(b, ks0a, ks1a); } while (0)
; #define SWRITE_B(b) do { *(bf16x8*)(V_lds + (b) * SHM_V + vst0) = vs0b; *(bf16x8*)(V_lds + (b) * SHM_V + vst1) = vs1b; KWRITE(b, ks0b, ks1b); } while (0)
; template <int ND0, int LDQ, int LDK, int LDO> ...
;     ...
;   f32x16 pA0, pA1, pB0, pB1; float mnA, mnB, alA, alB; bf16x8 pa0, pa1, pa2, pa3; const int NT = seq / KVBLK;
;   const char* Kq0 = K_lds + kofs; const char* Kq1 = K_lds + SHM_K + kofs;
;   if (ND0 == 4 && have_pf) { vs0a = pfv0; vs1a = pfv1; ks0a = pfk0; } else { SLOAD_A(0); }
;   asm volatile("s_waitcnt vmcnt(0)" ::: "memory"); SWRITE_A(0); __syncthreads();
;   qkt<ND0>(pA0, pA1, Kq0, qr, r32, hi); PSM(pA0, pA1, mnA, alA);
;   SLOAD_B(KVBLK); if (2 < NT) SLOAD_A(2 * KVBLK);
;   SWAIT(); SWRITE_B(1); __syncthreads();
;   for (int j = 1; j + 1 < NT; j += 2) {
;     SBAR(); qkt<ND0>(pB0, pB1, Kq1, qr, r32, hi);
;     finishSM(pA0, pA1, alA, l_reg, pa0, pa1, pa2, pa3); SBAR();
;     SLOAD_B((j + 2) * KVBLK); SBAR();
;     pv_d0(o, vb0, pa0, pa1, pa2, pa3); KWRITE(0, ks0a, ks1a); PSM(pB0, pB1, mnB, alB);
;     __syncthreads(); SWAIT(); VWRITE_A(0);
;     RESC(alB); __syncthreads();
;     SBAR(); qkt<ND0>(pA0, pA1, Kq0, qr, r32, hi);
;     finishSM(pB0, pB1, alB, l_reg, pa0, pa1, pa2, pa3); SBAR();
;     if (j + 3 < NT) SLOAD_A((j + 3) * KVBLK); SBAR();
;     pv_d0(o, vb0 + (int)SHM_V, pa0, pa1, pa2, pa3); KWRITE(1, ks0b, ks1b); PSM(pA0, pA1, mnA, alA);
.LBB0_216:
	v_exp_f32_e32 v219, v96
	v_exp_f32_e32 v221, v97
	v_exp_f32_e32 v217, v98
	v_exp_f32_e32 v220, v99
	v_exp_f32_e32 v215, v100
	v_exp_f32_e32 v218, v101
	v_exp_f32_e32 v214, v102
	v_exp_f32_e32 v216, v103
	v_exp_f32_e32 v211, v104
	v_exp_f32_e32 v213, v105
	v_exp_f32_e32 v209, v106
	v_exp_f32_e32 v212, v107
	v_exp_f32_e32 v207, v108
	v_exp_f32_e32 v210, v109
	v_exp_f32_e32 v206, v110
	v_exp_f32_e32 v208, v111
	s_waitcnt lgkmcnt(0)
	s_barrier
	ds_read_b128 v[64:67], v197 offset:32768
	ds_read_b128 v[68:71], v197 offset:40960
	s_waitcnt vmcnt(3)
	v_cmp_gt_f32_e32 vcc, 1.0, v203
	s_waitcnt vmcnt(3)
	ds_write_b128 v193, v[130:133]
	ds_write_b128 v194, v[134:137]
	s_cbranch_vccz .LBB0_220
	s_and_saveexec_b64 s[18:19], s[6:7]
	ds_write_b32 v187, v203 offset:128
	s_or_b64 exec, exec, s[18:19]
	s_waitcnt lgkmcnt(0)
	v_add_u32_e32 v76, v161, v112
	ds_read_b128 v[64:67], v76 offset:224
	ds_read_b128 v[68:71], v76 offset:192
	ds_read_b128 v[72:75], v76 offset:160
	ds_read_b128 v[76:79], v76 offset:128
	s_waitcnt lgkmcnt(3)
	v_pk_mul_f32 v[12:13], v[12:13], v[64:65]
	s_waitcnt lgkmcnt(2)
	v_pk_mul_f32 v[8:9], v[8:9], v[68:69]
	s_waitcnt lgkmcnt(1)
	v_pk_mul_f32 v[4:5], v[4:5], v[72:73]
	v_pk_mul_f32 v[14:15], v[14:15], v[66:67]
	v_pk_mul_f32 v[10:11], v[10:11], v[70:71]
	v_pk_mul_f32 v[6:7], v[6:7], v[74:75]
	s_waitcnt lgkmcnt(0)
	v_pk_mul_f32 v[2:3], v[2:3], v[78:79]
	v_pk_mul_f32 v[0:1], v[0:1], v[76:77]
	v_pk_mul_f32 v[60:61], v[60:61], v[64:65]
	v_pk_mul_f32 v[56:57], v[56:57], v[68:69]
	v_pk_mul_f32 v[52:53], v[52:53], v[72:73]
	v_pk_mul_f32 v[62:63], v[62:63], v[66:67]
	v_pk_mul_f32 v[58:59], v[58:59], v[70:71]
	v_pk_mul_f32 v[54:55], v[54:55], v[74:75]
	v_pk_mul_f32 v[50:51], v[50:51], v[78:79]
	v_pk_mul_f32 v[48:49], v[48:49], v[76:77]
	v_pk_mul_f32 v[44:45], v[44:45], v[64:65]
	v_pk_mul_f32 v[40:41], v[40:41], v[68:69]
	v_pk_mul_f32 v[36:37], v[36:37], v[72:73]
	v_pk_mul_f32 v[46:47], v[46:47], v[66:67]
	v_pk_mul_f32 v[42:43], v[42:43], v[70:71]
	v_pk_mul_f32 v[38:39], v[38:39], v[74:75]
	v_pk_mul_f32 v[34:35], v[34:35], v[78:79]
	v_pk_mul_f32 v[32:33], v[32:33], v[76:77]
	v_pk_mul_f32 v[28:29], v[28:29], v[64:65]
	v_pk_mul_f32 v[24:25], v[24:25], v[68:69]
	v_pk_mul_f32 v[20:21], v[20:21], v[72:73]
	v_pk_mul_f32 v[30:31], v[30:31], v[66:67]
	v_pk_mul_f32 v[26:27], v[26:27], v[70:71]
	v_pk_mul_f32 v[22:23], v[22:23], v[74:75]
	v_pk_mul_f32 v[18:19], v[18:19], v[78:79]
	v_pk_mul_f32 v[16:17], v[16:17], v[76:77]
	ds_read_b128 v[64:67], v197 offset:32768
	ds_read_b128 v[68:71], v197 offset:40960
	s_waitcnt lgkmcnt(0)
.LBB0_220:
	ds_read_b128 v[222:225], v198 offset:32768
	ds_read_b128 v[244:247], v198 offset:40960
	ds_read_b128 v[130:133], v199 offset:32768
	ds_read_b128 v[134:137], v199 offset:40960
	ds_read_b128 v[138:141], v196 offset:32768
	v_exp_f32_e32 v226, v84
	v_exp_f32_e32 v227, v85
	s_waitcnt lgkmcnt(5)
	v_mfma_f32_32x32x16_bf16 v[96:111], v[64:67], v[126:129], 0
	v_exp_f32_e32 v234, v86
	v_exp_f32_e32 v235, v87
	v_exp_f32_e32 v236, v88
	v_exp_f32_e32 v237, v89
	v_exp_f32_e32 v238, v90
	v_exp_f32_e32 v239, v91
	v_exp_f32_e32 v240, v92
	v_mfma_f32_32x32x16_bf16 v[64:79], v[68:71], v[126:129], 0
	v_exp_f32_e32 v241, v93
	v_exp_f32_e32 v95, v95
	s_waitcnt lgkmcnt(3)
	v_mfma_f32_32x32x16_bf16 v[96:111], v[222:225], v[122:125], v[96:111]
	v_mfma_f32_32x32x16_bf16 v[64:79], v[244:247], v[122:125], v[64:79]
	ds_read_b128 v[244:247], v196 offset:40960
	s_waitcnt lgkmcnt(2)
	v_mfma_f32_32x32x16_bf16 v[96:111], v[130:133], v[118:121], v[96:111]
	v_mfma_f32_32x32x16_bf16 v[64:79], v[134:137], v[118:121], v[64:79]
	s_waitcnt lgkmcnt(0)
	v_mfma_f32_32x32x16_bf16 v[96:111], v[138:141], v[114:117], v[96:111]
	v_exp_f32_e32 v222, v80
	v_add_f32_e32 v80, 0, v219
	v_add_f32_e32 v80, v221, v80
	v_add_f32_e32 v80, v217, v80
	v_add_f32_e32 v80, v220, v80
	v_add_f32_e32 v80, v215, v80
	v_add_f32_e32 v80, v218, v80
	v_add_f32_e32 v80, v214, v80
	v_add_f32_e32 v80, v216, v80
	v_add_f32_e32 v80, v211, v80
	v_add_f32_e32 v80, v213, v80
	v_add_f32_e32 v80, v209, v80
	v_add_f32_e32 v80, v212, v80
	v_add_f32_e32 v80, v207, v80
	v_exp_f32_e32 v223, v81
	v_add_f32_e32 v80, v210, v80
	v_exp_f32_e32 v224, v82
	v_add_f32_e32 v80, v206, v80
	v_exp_f32_e32 v225, v83
	v_add_f32_e32 v80, v208, v80
	v_add_f32_e32 v80, v222, v80
	v_add_f32_e32 v80, v223, v80
	v_add_f32_e32 v80, v224, v80
	v_add_f32_e32 v80, v225, v80
	v_add_f32_e32 v80, v226, v80
	v_add_f32_e32 v80, v227, v80
	v_add_f32_e32 v80, v234, v80
	v_add_f32_e32 v80, v235, v80
	v_add_f32_e32 v80, v236, v80
	v_add_f32_e32 v80, v237, v80
	v_mfma_f32_32x32x16_bf16 v[64:79], v[244:247], v[114:117], v[64:79]
	v_exp_f32_e32 v244, v94
	v_add_f32_e32 v80, v238, v80
	v_add_f32_e32 v80, v239, v80
	v_add_f32_e32 v80, v240, v80
	v_add_f32_e32 v80, v241, v80
	v_add_f32_e32 v80, v244, v80
	v_add_f32_e32 v204, v95, v80
	v_mov_b32_e32 v205, v204
	v_cvt_pk_bf16_f32 v80, v219, v221
	v_cvt_pk_bf16_f32 v81, v217, v220
	v_cvt_pk_bf16_f32 v82, v215, v218
	v_cvt_pk_bf16_f32 v83, v214, v216
	v_cvt_pk_bf16_f32 v84, v211, v213
	v_cvt_pk_bf16_f32 v85, v209, v212
	v_cvt_pk_bf16_f32 v86, v207, v210
	v_cvt_pk_bf16_f32 v87, v206, v208
	v_cvt_pk_bf16_f32 v88, v222, v223
	v_cvt_pk_bf16_f32 v89, v224, v225
	v_cvt_pk_bf16_f32 v90, v226, v227
	v_cvt_pk_bf16_f32 v91, v234, v235
	v_cvt_pk_bf16_f32 v92, v236, v237
	v_cvt_pk_bf16_f32 v93, v238, v239
	v_cvt_pk_bf16_f32 v94, v240, v241
	v_cvt_pk_bf16_f32 v95, v244, v95
	v_permlane32_swap_b32_e32 v204, v205
	v_permlane32_swap_b32_e32 v80, v82
	v_permlane32_swap_b32_e32 v81, v83
	v_permlane32_swap_b32_e32 v84, v86
	v_permlane32_swap_b32_e32 v85, v87
	v_permlane32_swap_b32_e32 v88, v90
	v_permlane32_swap_b32_e32 v89, v91
	v_permlane32_swap_b32_e32 v92, v94
	v_permlane32_swap_b32_e32 v93, v95
	s_cmp_ge_u32 s40, s39
	s_cselect_b64 s[18:19], -1, 0
	s_and_b64 vcc, exec, s[18:19]
	s_cbranch_vccnz .Ldiff_pf_skip
	v_add_co_u32_e32 v130, vcc, 0x13281000, v174
	s_nop 1
	v_addc_co_u32_e32 v131, vcc, 0, v175, vcc
	v_add_co_u32_e32 v134, vcc, 0x132b1000, v174
	s_nop 1
	v_addc_co_u32_e32 v135, vcc, 0, v175, vcc
	v_add_co_u32_e32 v138, vcc, 0x13280000, v176
	global_load_dwordx4 v[130:133], v[130:131], off
	global_load_dwordx4 v[134:137], v[134:135], off
	v_addc_co_u32_e32 v139, vcc, 0, v177, vcc
	global_load_dwordx4 v[138:141], v[138:139], off offset:2048

; #define SBAR() __builtin_amdgcn_sched_barrier(0)
; #define KWRITE(b, src0, src1) do { if constexpr (ND0 == 4) { *(bf16x8*)(K_lds + (b) * SHM_K + KSWZ(kr, kcb)) = src0; } \
;     else { int kc = sc * 2; *(bf16x8*)(K_lds + (b) * SHM_K + KSWZ(sr, kc)) = src0; *(bf16x8*)(K_lds + (b) * SHM_K + KSWZ(32 + sr, kc)) = src1; } } while (0)
; #define SLOAD_A(k0) do { vs0a = *reinterpret_cast<const bf16x8*>(&Vh[(long)((k0) + sr) * LDK + sc]); vs1a = *reinterpret_cast<const bf16x8*>(&Vh[(long)((k0) + 32 + sr) * LDK + sc]); KLOAD(ks0a, ks1a, k0); } while (0)
; #define SLOAD_B(k0) do { vs0b = *reinterpret_cast<const bf16x8*>(&Vh[(long)((k0) + sr) * LDK + sc]); vs1b = *reinterpret_cast<const bf16x8*>(&Vh[(long)((k0) + 32 + sr) * LDK + sc]); KLOAD(ks0b, ks1b, k0); } while (0)
; #define SWRITE_A(b) do { *(bf16x8*)(V_lds + (b) * SHM_V + vst0) = vs0a; *(bf16x8*)(V_lds + (b) * SHM_V + vst1) = vs1a; KWRITE(b, ks0a, ks1a); } while (0)
; #define SWRITE_B(b) do { *(bf16x8*)(V_lds + (b) * SHM_V + vst0) = vs0b; *(bf16x8*)(V_lds + (b) * SHM_V + vst1) = vs1b; KWRITE(b, ks0b, ks1b); } while (0)
; template <int ND0, int LDQ, int LDK, int LDO> ...
;     ...
;   f32x16 pA0, pA1, pB0, pB1; float mnA, mnB, alA, alB; bf16x8 pa0, pa1, pa2, pa3; const int NT = seq / KVBLK;
;   const char* Kq0 = K_lds + kofs; const char* Kq1 = K_lds + SHM_K + kofs;
;   if (ND0 == 4 && have_pf) { vs0a = pfv0; vs1a = pfv1; ks0a = pfk0; } else { SLOAD_A(0); }
;   asm volatile("s_waitcnt vmcnt(0)" ::: "memory"); SWRITE_A(0); __syncthreads();
;   qkt<ND0>(pA0, pA1, Kq0, qr, r32, hi); PSM(pA0, pA1, mnA, alA);
;   SLOAD_B(KVBLK); if (2 < NT) SLOAD_A(2 * KVBLK);
;   SWAIT(); SWRITE_B(1); __syncthreads();
;   for (int j = 1; j + 1 < NT; j += 2) {
;     SBAR(); qkt<ND0>(pB0, pB1, Kq1, qr, r32, hi);
;     finishSM(pA0, pA1, alA, l_reg, pa0, pa1, pa2, pa3); SBAR();
;     SLOAD_B((j + 2) * KVBLK); SBAR();
;     pv_d0(o, vb0, pa0, pa1, pa2, pa3); KWRITE(0, ks0a, ks1a); PSM(pB0, pB1, mnB, alB);
;     __syncthreads(); SWAIT(); VWRITE_A(0);
;     RESC(alB); __syncthreads();
;     SBAR(); qkt<ND0>(pA0, pA1, Kq0, qr, r32, hi);
;     finishSM(pB0, pB1, alB, l_reg, pa0, pa1, pa2, pa3); SBAR();
;     if (j + 3 < NT) SLOAD_A((j + 3) * KVBLK); SBAR();
;     pv_d0(o, vb0 + (int)SHM_V, pa0, pa1, pa2, pa3); KWRITE(1, ks0b, ks1b); PSM(pA0, pA1, mnA, alA);
;     __syncthreads(); SWAIT(); VWRITE_B(1);
;     RESC(alA); __syncthreads();
;   }
.LBB0_224:
	v_exp_f32_e32 v176, v96
	v_exp_f32_e32 v206, v97
	v_exp_f32_e32 v174, v98
	v_exp_f32_e32 v177, v99
	v_exp_f32_e32 v152, v100
	v_exp_f32_e32 v175, v101
	v_exp_f32_e32 v151, v102
	v_exp_f32_e32 v153, v103
	v_add_f32_e32 v80, v201, v202
	v_fmac_f32_e32 v80, v200, v189
	v_add_f32_e32 v189, v204, v205
	v_fmac_f32_e32 v189, v80, v203
	s_waitcnt lgkmcnt(0)
	s_barrier
	ds_read_b128 v[80:83], v197 offset:49152
	ds_read_b128 v[84:87], v197 offset:57344
	s_waitcnt vmcnt(3)
	v_cmp_gt_f32_e32 vcc, 1.0, v150
	ds_write_b128 v193, v[142:145] offset:16384
	ds_write_b128 v194, v[146:149] offset:16384
	s_cbranch_vccz .LBB0_228
	s_and_saveexec_b64 s[20:21], s[6:7]
	ds_write_b32 v187, v150 offset:128
	s_or_b64 exec, exec, s[20:21]
	s_waitcnt lgkmcnt(0)
	v_add_u32_e32 v92, v161, v112
	ds_read_b128 v[80:83], v92 offset:224
	ds_read_b128 v[84:87], v92 offset:192
	ds_read_b128 v[88:91], v92 offset:160
	ds_read_b128 v[92:95], v92 offset:128
	s_waitcnt lgkmcnt(3)
	v_pk_mul_f32 v[12:13], v[12:13], v[80:81]
	s_waitcnt lgkmcnt(2)
	v_pk_mul_f32 v[8:9], v[8:9], v[84:85]
	s_waitcnt lgkmcnt(1)
	v_pk_mul_f32 v[4:5], v[4:5], v[88:89]
	v_pk_mul_f32 v[14:15], v[14:15], v[82:83]
	v_pk_mul_f32 v[10:11], v[10:11], v[86:87]
	v_pk_mul_f32 v[6:7], v[6:7], v[90:91]
	s_waitcnt lgkmcnt(0)
	v_pk_mul_f32 v[2:3], v[2:3], v[94:95]
	v_pk_mul_f32 v[0:1], v[0:1], v[92:93]
	v_pk_mul_f32 v[60:61], v[60:61], v[80:81]
	v_pk_mul_f32 v[56:57], v[56:57], v[84:85]
	v_pk_mul_f32 v[52:53], v[52:53], v[88:89]
	v_pk_mul_f32 v[62:63], v[62:63], v[82:83]
	v_pk_mul_f32 v[58:59], v[58:59], v[86:87]
	v_pk_mul_f32 v[54:55], v[54:55], v[90:91]
	v_pk_mul_f32 v[50:51], v[50:51], v[94:95]
	v_pk_mul_f32 v[48:49], v[48:49], v[92:93]
	v_pk_mul_f32 v[44:45], v[44:45], v[80:81]
	v_pk_mul_f32 v[40:41], v[40:41], v[84:85]
	v_pk_mul_f32 v[36:37], v[36:37], v[88:89]
	v_pk_mul_f32 v[46:47], v[46:47], v[82:83]
	v_pk_mul_f32 v[42:43], v[42:43], v[86:87]
	v_pk_mul_f32 v[38:39], v[38:39], v[90:91]
	v_pk_mul_f32 v[34:35], v[34:35], v[94:95]
	v_pk_mul_f32 v[32:33], v[32:33], v[92:93]
	v_pk_mul_f32 v[28:29], v[28:29], v[80:81]
	v_pk_mul_f32 v[24:25], v[24:25], v[84:85]
	v_pk_mul_f32 v[20:21], v[20:21], v[88:89]
	v_pk_mul_f32 v[30:31], v[30:31], v[82:83]
	v_pk_mul_f32 v[26:27], v[26:27], v[86:87]
	v_pk_mul_f32 v[22:23], v[22:23], v[90:91]
	v_pk_mul_f32 v[18:19], v[18:19], v[94:95]
	v_pk_mul_f32 v[16:17], v[16:17], v[92:93]
	ds_read_b128 v[80:83], v197 offset:49152
	ds_read_b128 v[84:87], v197 offset:57344
	s_waitcnt lgkmcnt(0)
.LBB0_228:
	v_exp_f32_e32 v147, v104
	v_exp_f32_e32 v149, v105
	v_exp_f32_e32 v145, v106
	v_exp_f32_e32 v148, v107
	v_exp_f32_e32 v143, v108
	v_exp_f32_e32 v146, v109
	v_exp_f32_e32 v142, v110
	v_exp_f32_e32 v144, v111
	v_lshl_add_u64 v[170:171], v[170:171], 0, s[46:47]
	v_lshl_add_u64 v[172:173], v[172:173], 0, s[46:47]
	s_add_i32 s40, s40, 2
	s_and_b64 vcc, exec, s[18:19]
	s_cbranch_vccnz .LBB0_234
	v_mov_b32_e32 v200, v150
	s_branch .LBB0_214
